# cache-policy lever: f32 residual stream (X tile loads and stores in the three residual epilogues) marked non-temporal
# speedup vs baseline: 1.0279x; 1.0279x over previous
.LBB0_1000:
	s_lshl_b32 s0, s4, 5
	s_lshl_b32 s5, s53, 8
	s_lshl_b32 s1, s8, 8
	s_add_i32 s2, s5, s36
	s_or_b32 s0, s1, s0
	s_cmp_gt_i32 s53, 15
	v_lshl_or_b32 v162, v152, 3, s0
	s_cselect_b32 s0, 0x3000, 0
	s_lshl_b32 s12, s0, 2
	v_readlane_b32 s0, v255, 2
	v_readlane_b32 s1, v255, 3
	s_add_u32 s0, s0, s12
	v_ashrrev_i32_e32 v163, 31, v162
	s_addc_u32 s1, s1, 0
	v_lshlrev_b64 v[146:147], 2, v[162:163]
	v_lshl_add_u64 v[130:131], s[0:1], 0, v[146:147]
	s_movk_i32 s0, 0x4000
	v_or_b32_e32 v148, s2, v148
	v_lshl_add_u64 v[134:135], v[130:131], 0, s[26:27]
	v_add_co_u32_e32 v130, vcc, s0, v130
	v_ashrrev_i32_e32 v149, 31, v148
	v_readlane_b32 s0, v254, 61
	v_lshlrev_b64 v[150:151], 13, v[148:149]
	v_readlane_b32 s1, v254, 62
	v_addc_co_u32_e32 v131, vcc, 0, v131, vcc
	s_nop 0
	v_lshl_add_u64 v[150:151], s[0:1], 0, v[150:151]
	v_lshl_add_u64 v[150:151], v[150:151], 0, v[146:147]
	s_waitcnt vmcnt(0)
	s_barrier
	global_load_dwordx4 v[142:145], v[130:131], off
	global_load_dwordx4 v[138:141], v[134:135], off offset:16
	s_nop 0
	global_load_dwordx4 v[130:133], v[134:135], off offset:528
	s_nop 0
	global_load_dwordx4 v[134:137], v[134:135], off offset:512
	s_nop 0
	global_load_dwordx4 v[178:181], v[150:151], off offset:16 nt
	global_load_dwordx4 v[182:185], v[150:151], off nt
	global_load_dwordx4 v[186:189], v[150:151], off offset:528 nt
	global_load_dwordx4 v[190:193], v[150:151], off offset:512 nt
	v_add_co_u32_e32 v164, vcc, 0x20000, v150
	s_nop 1
	v_addc_co_u32_e32 v165, vcc, 0, v151, vcc
	global_load_dwordx4 v[198:201], v[164:165], off offset:16 nt
	global_load_dwordx4 v[202:205], v[164:165], off nt
	global_load_dwordx4 v[206:209], v[164:165], off offset:528 nt
	global_load_dwordx4 v[214:217], v[164:165], off offset:512 nt
	v_add_co_u32_e32 v164, vcc, 0x40000, v150
	s_nop 1
	v_addc_co_u32_e32 v165, vcc, 0, v151, vcc
	global_load_dwordx4 v[218:221], v[164:165], off offset:16 nt
	global_load_dwordx4 v[222:225], v[164:165], off nt
	global_load_dwordx4 v[226:229], v[164:165], off offset:528 nt
	global_load_dwordx4 v[230:233], v[164:165], off offset:512 nt
	v_add_co_u32_e32 v164, vcc, 0x60000, v150
	s_nop 1
	v_addc_co_u32_e32 v165, vcc, 0, v151, vcc
	global_load_dwordx4 v[234:237], v[164:165], off offset:16 nt
	global_load_dwordx4 v[238:241], v[164:165], off nt
	global_load_dwordx4 v[242:245], v[164:165], off offset:528 nt
	global_load_dwordx4 v[154:157], v[164:165], off offset:512 nt
	s_waitcnt vmcnt(15)
	v_pk_fma_f32 v[108:109], v[108:109], v[140:141], v[180:181]
	v_pk_fma_f32 v[106:107], v[106:107], v[138:139], v[178:179]
	v_add_co_u32_e32 v164, vcc, 0x100000, v150
	s_nop 1
	v_addc_co_u32_e32 v165, vcc, 0, v151, vcc
	global_load_dwordx4 v[178:181], v[164:165], off nt
	s_waitcnt vmcnt(15)
	v_pk_fma_f32 v[112:113], v[112:113], v[144:145], v[184:185]
	v_pk_fma_f32 v[110:111], v[110:111], v[142:143], v[182:183]
	global_load_dwordx4 v[182:185], v[164:165], off offset:16 nt
	s_waitcnt vmcnt(15)
	v_pk_fma_f32 v[0:1], v[0:1], v[130:131], v[186:187]
	v_pk_fma_f32 v[2:3], v[2:3], v[132:133], v[188:189]
	global_load_dwordx4 v[186:189], v[164:165], off offset:528 nt
	s_waitcnt vmcnt(15)
	v_pk_fma_f32 v[6:7], v[6:7], v[136:137], v[192:193]
	v_pk_fma_f32 v[4:5], v[4:5], v[134:135], v[190:191]
	global_load_dwordx4 v[190:193], v[164:165], off offset:512 nt
	s_waitcnt vmcnt(15)
	v_pk_fma_f32 v[116:117], v[116:117], v[140:141], v[200:201]
	v_pk_fma_f32 v[114:115], v[114:115], v[138:139], v[198:199]
	v_add_co_u32_e32 v164, vcc, 0x120000, v150
	s_nop 1
	v_addc_co_u32_e32 v165, vcc, 0, v151, vcc
	global_load_dwordx4 v[198:201], v[164:165], off nt
	s_waitcnt vmcnt(15)
	v_pk_fma_f32 v[120:121], v[120:121], v[144:145], v[204:205]
	v_pk_fma_f32 v[118:119], v[118:119], v[142:143], v[202:203]
	global_load_dwordx4 v[202:205], v[164:165], off offset:16 nt
	s_waitcnt vmcnt(15)
	v_pk_fma_f32 v[8:9], v[8:9], v[130:131], v[206:207]
	v_pk_fma_f32 v[10:11], v[10:11], v[132:133], v[208:209]
	global_load_dwordx4 v[206:209], v[164:165], off offset:528 nt
	s_waitcnt vmcnt(15)
	v_pk_fma_f32 v[14:15], v[14:15], v[136:137], v[216:217]
	v_pk_fma_f32 v[12:13], v[12:13], v[134:135], v[214:215]
	global_load_dwordx4 v[214:217], v[164:165], off offset:512 nt
	s_waitcnt vmcnt(15)
	v_pk_fma_f32 v[124:125], v[124:125], v[140:141], v[220:221]
	v_pk_fma_f32 v[122:123], v[122:123], v[138:139], v[218:219]
	v_add_co_u32_e32 v164, vcc, 0x140000, v150
	s_nop 1
	v_addc_co_u32_e32 v165, vcc, 0, v151, vcc
	global_load_dwordx4 v[218:221], v[164:165], off nt
	s_waitcnt vmcnt(15)
	v_pk_fma_f32 v[128:129], v[128:129], v[144:145], v[224:225]
	v_pk_fma_f32 v[126:127], v[126:127], v[142:143], v[222:223]
	global_load_dwordx4 v[222:225], v[164:165], off offset:16 nt
	s_waitcnt vmcnt(15)
	v_pk_fma_f32 v[20:21], v[20:21], v[130:131], v[226:227]
	v_pk_fma_f32 v[22:23], v[22:23], v[132:133], v[228:229]
	global_load_dwordx4 v[226:229], v[164:165], off offset:528 nt
	s_waitcnt vmcnt(15)
	v_pk_fma_f32 v[26:27], v[26:27], v[136:137], v[232:233]
	v_pk_fma_f32 v[24:25], v[24:25], v[134:135], v[230:231]
	global_load_dwordx4 v[230:233], v[164:165], off offset:512 nt
	s_waitcnt vmcnt(15)
	v_pk_fma_f32 v[90:91], v[90:91], v[140:141], v[236:237]
	v_pk_fma_f32 v[88:89], v[88:89], v[138:139], v[234:235]
	v_add_co_u32_e32 v164, vcc, 0x160000, v150
	s_nop 1
	v_addc_co_u32_e32 v165, vcc, 0, v151, vcc
	global_load_dwordx4 v[234:237], v[164:165], off nt
	s_waitcnt vmcnt(15)
	v_pk_fma_f32 v[94:95], v[94:95], v[144:145], v[240:241]
	v_pk_fma_f32 v[92:93], v[92:93], v[142:143], v[238:239]
	global_load_dwordx4 v[238:241], v[164:165], off offset:16 nt
	s_waitcnt vmcnt(15)
	v_pk_fma_f32 v[34:35], v[34:35], v[132:133], v[244:245]
	v_pk_fma_f32 v[32:33], v[32:33], v[130:131], v[242:243]
	global_load_dwordx4 v[242:245], v[164:165], off offset:528 nt
	s_waitcnt vmcnt(15)
	v_pk_fma_f32 v[42:43], v[42:43], v[136:137], v[156:157]
	v_pk_fma_f32 v[40:41], v[40:41], v[134:135], v[154:155]
	global_load_dwordx4 v[154:157], v[164:165], off offset:512 nt
	s_waitcnt vmcnt(15)
	v_pk_fma_f32 v[104:105], v[104:105], v[144:145], v[180:181]
	v_pk_fma_f32 v[102:103], v[102:103], v[142:143], v[178:179]
	s_waitcnt vmcnt(14)
	v_pk_fma_f32 v[100:101], v[100:101], v[140:141], v[184:185]
	v_pk_fma_f32 v[98:99], v[98:99], v[138:139], v[182:183]
	s_waitcnt vmcnt(13)
	v_pk_fma_f32 v[56:57], v[56:57], v[130:131], v[186:187]
	v_pk_fma_f32 v[58:59], v[58:59], v[132:133], v[188:189]
	s_waitcnt vmcnt(12)
	v_pk_fma_f32 v[62:63], v[62:63], v[136:137], v[192:193]
	v_pk_fma_f32 v[60:61], v[60:61], v[134:135], v[190:191]
	s_waitcnt vmcnt(11)
	v_pk_fma_f32 v[86:87], v[86:87], v[144:145], v[200:201]
	v_pk_fma_f32 v[84:85], v[84:85], v[142:143], v[198:199]
	s_waitcnt vmcnt(10)
	v_pk_fma_f32 v[82:83], v[82:83], v[140:141], v[204:205]
	v_pk_fma_f32 v[80:81], v[80:81], v[138:139], v[202:203]
	s_waitcnt vmcnt(9)
	v_pk_fma_f32 v[72:73], v[72:73], v[130:131], v[206:207]
	v_pk_fma_f32 v[74:75], v[74:75], v[132:133], v[208:209]
	s_waitcnt vmcnt(8)
	v_pk_fma_f32 v[78:79], v[78:79], v[136:137], v[216:217]
	v_pk_fma_f32 v[76:77], v[76:77], v[134:135], v[214:215]
	s_waitcnt vmcnt(7)
	v_pk_fma_f32 v[70:71], v[70:71], v[144:145], v[220:221]
	v_pk_fma_f32 v[68:69], v[68:69], v[142:143], v[218:219]
	s_waitcnt vmcnt(6)
	v_pk_fma_f32 v[66:67], v[66:67], v[140:141], v[224:225]
	v_pk_fma_f32 v[64:65], v[64:65], v[138:139], v[222:223]
	s_waitcnt vmcnt(5)
	v_pk_fma_f32 v[50:51], v[50:51], v[132:133], v[228:229]
	v_pk_fma_f32 v[48:49], v[48:49], v[130:131], v[226:227]
	s_waitcnt vmcnt(4)
	v_pk_fma_f32 v[54:55], v[54:55], v[136:137], v[232:233]
	v_pk_fma_f32 v[52:53], v[52:53], v[134:135], v[230:231]
	s_waitcnt vmcnt(3)
	v_pk_fma_f32 v[46:47], v[46:47], v[144:145], v[236:237]
	v_pk_fma_f32 v[44:45], v[44:45], v[142:143], v[234:235]
	s_waitcnt vmcnt(2)
	v_pk_fma_f32 v[38:39], v[38:39], v[140:141], v[240:241]
	v_pk_fma_f32 v[36:37], v[36:37], v[138:139], v[238:239]
	s_waitcnt vmcnt(1)
	v_pk_fma_f32 v[18:19], v[18:19], v[132:133], v[244:245]
	v_pk_fma_f32 v[16:17], v[16:17], v[130:131], v[242:243]
	s_waitcnt vmcnt(0)
	v_pk_fma_f32 v[28:29], v[28:29], v[134:135], v[154:155]
	v_pk_fma_f32 v[30:31], v[30:31], v[136:137], v[156:157]
	s_mov_b64 s[0:1], 0x160000
	s_branch .Lmy_pad_1
	s_nop 0
	s_nop 0
	s_nop 0
	s_nop 0
	s_nop 0
	s_nop 0
	s_nop 0
	s_nop 0
	s_nop 0
	s_nop 0
	s_nop 0
	s_nop 0
	s_nop 0
	s_nop 0
	s_nop 0
	s_nop 0
	s_nop 0
	s_nop 0
	s_nop 0
	s_nop 0
	s_nop 0
	s_nop 0
	s_nop 0
	s_nop 0
	s_nop 0
	s_nop 0
	s_nop 0
	s_nop 0
	s_nop 0
	s_nop 0
	s_nop 0
	s_nop 0
	s_nop 0
	s_nop 0
	s_nop 0
	s_nop 0
	s_nop 0
	s_nop 0
	s_nop 0
	s_nop 0
	s_nop 0
	s_nop 0
	s_nop 0
	s_nop 0
	s_nop 0
	s_nop 0
	s_nop 0
	s_nop 0

.LBB0_1021:
	s_or_b64 exec, exec, s[8:9]
	s_mov_b64 s[2:3], 0x20000
	v_ashrrev_i32_e32 v149, 31, v148
	v_lshlrev_b64 v[134:135], 13, v[148:149]
	v_lshl_add_u64 v[134:135], s[96:97], 0, v[134:135]
	v_lshl_add_u64 v[134:135], v[162:163], 2, v[134:135]
	v_mov_b64_e32 v[136:137], v[134:135]
	flat_store_dwordx4 v[136:137], v[110:113] nt
	flat_store_dwordx4 v[136:137], v[106:109] offset:16 nt
	flat_store_dwordx4 v[136:137], v[4:7] offset:512 nt
	flat_store_dwordx4 v[136:137], v[0:3] offset:528 nt
	v_lshl_add_u64 v[136:137], v[134:135], 0, s[2:3]
	s_mov_b64 s[2:3], 0x40000
	flat_store_dwordx4 v[136:137], v[118:121] nt
	flat_store_dwordx4 v[136:137], v[114:117] offset:16 nt
	flat_store_dwordx4 v[136:137], v[12:15] offset:512 nt
	flat_store_dwordx4 v[136:137], v[8:11] offset:528 nt
	v_lshl_add_u64 v[136:137], v[134:135], 0, s[2:3]
	s_mov_b64 s[2:3], 0x60000
	flat_store_dwordx4 v[136:137], v[126:129] nt
	flat_store_dwordx4 v[136:137], v[122:125] offset:16 nt
	flat_store_dwordx4 v[136:137], v[24:27] offset:512 nt
	flat_store_dwordx4 v[136:137], v[20:23] offset:528 nt
	v_lshl_add_u64 v[136:137], v[134:135], 0, s[2:3]
	s_mov_b64 s[2:3], 0x100000
	flat_store_dwordx4 v[136:137], v[92:95] nt
	flat_store_dwordx4 v[136:137], v[88:91] offset:16 nt
	flat_store_dwordx4 v[136:137], v[40:43] offset:512 nt
	flat_store_dwordx4 v[136:137], v[32:35] offset:528 nt
	v_lshl_add_u64 v[136:137], v[134:135], 0, s[2:3]
	s_mov_b64 s[2:3], 0x120000
	flat_store_dwordx4 v[136:137], v[102:105] nt
	flat_store_dwordx4 v[136:137], v[98:101] offset:16 nt
	flat_store_dwordx4 v[136:137], v[60:63] offset:512 nt
	flat_store_dwordx4 v[136:137], v[56:59] offset:528 nt
	v_lshl_add_u64 v[136:137], v[134:135], 0, s[2:3]
	s_mov_b64 s[2:3], 0x140000
	flat_store_dwordx4 v[136:137], v[84:87] nt
	flat_store_dwordx4 v[136:137], v[80:83] offset:16 nt
	flat_store_dwordx4 v[136:137], v[76:79] offset:512 nt
	flat_store_dwordx4 v[136:137], v[72:75] offset:528 nt
	v_lshl_add_u64 v[136:137], v[134:135], 0, s[2:3]
	s_mov_b64 s[2:3], 0x160000
	v_lshl_add_u64 v[134:135], v[134:135], 0, s[2:3]
	flat_store_dwordx4 v[136:137], v[68:71] nt
	flat_store_dwordx4 v[136:137], v[64:67] offset:16 nt
	flat_store_dwordx4 v[136:137], v[52:55] offset:512 nt
	flat_store_dwordx4 v[136:137], v[48:51] offset:528 nt
	s_cmp_gt_u32 s40, 63
	flat_store_dwordx4 v[134:135], v[44:47] nt
	flat_store_dwordx4 v[134:135], v[36:39] offset:16 nt
	flat_store_dwordx4 v[134:135], v[28:31] offset:512 nt
	flat_store_dwordx4 v[134:135], v[16:19] offset:528 nt
	s_cbranch_scc1 .LBB0_1027
	s_lshl_b32 s8, s53, 4
	s_lshl_b32 s2, s60, 7
	s_ashr_i32 s9, s8, 31
	s_or_b32 s2, s2, 64
	s_lshl_b64 s[8:9], s[8:9], 2
	v_readlane_b32 s3, v252, 39
	s_add_u32 s8, s3, s8
	v_readlane_b32 s3, v252, 40
	s_addc_u32 s9, s3, s9
	s_mov_b32 s3, 0x100001
	s_branch .LBB0_1024

.LBB0_1364:
	s_lshl_b32 s0, s4, 5
	s_lshl_b32 s5, s51, 8
	s_lshl_b32 s1, s8, 8
	s_add_i32 s2, s5, s36
	s_or_b32 s0, s1, s0
	s_cmp_gt_i32 s51, 15
	v_lshl_or_b32 v162, v152, 3, s0
	s_cselect_b32 s0, 0x3000, 0
	v_or_b32_e32 v148, s2, v148
	s_lshl_b32 s12, s0, 2
	v_ashrrev_i32_e32 v149, 31, v148
	s_add_u32 s0, s49, s12
	v_ashrrev_i32_e32 v163, 31, v162
	v_lshlrev_b64 v[150:151], 13, v[148:149]
	s_addc_u32 s1, s50, 0
	v_lshlrev_b64 v[146:147], 2, v[162:163]
	v_lshl_add_u64 v[150:151], s[96:97], 0, v[150:151]
	v_lshl_add_u64 v[134:135], s[0:1], 0, v[146:147]
	v_lshl_add_u64 v[150:151], v[150:151], 0, v[146:147]
	s_waitcnt vmcnt(0)
	s_barrier
	global_load_dwordx4 v[138:141], v[134:135], off offset:16
	global_load_dwordx4 v[142:145], v[134:135], off
	global_load_dwordx4 v[130:133], v[134:135], off offset:528
	s_nop 0
	global_load_dwordx4 v[134:137], v[134:135], off offset:512
	s_nop 0
	global_load_dwordx4 v[178:181], v[150:151], off offset:16 nt
	global_load_dwordx4 v[182:185], v[150:151], off nt
	global_load_dwordx4 v[186:189], v[150:151], off offset:528 nt
	global_load_dwordx4 v[190:193], v[150:151], off offset:512 nt
	v_add_co_u32_e32 v164, vcc, 0x20000, v150
	s_nop 1
	v_addc_co_u32_e32 v165, vcc, 0, v151, vcc
	global_load_dwordx4 v[198:201], v[164:165], off offset:16 nt
	global_load_dwordx4 v[202:205], v[164:165], off nt
	global_load_dwordx4 v[206:209], v[164:165], off offset:528 nt
	global_load_dwordx4 v[214:217], v[164:165], off offset:512 nt
	v_add_co_u32_e32 v164, vcc, 0x40000, v150
	s_nop 1
	v_addc_co_u32_e32 v165, vcc, 0, v151, vcc
	global_load_dwordx4 v[218:221], v[164:165], off offset:16 nt
	global_load_dwordx4 v[222:225], v[164:165], off nt
	global_load_dwordx4 v[226:229], v[164:165], off offset:528 nt
	global_load_dwordx4 v[230:233], v[164:165], off offset:512 nt
	v_add_co_u32_e32 v164, vcc, 0x60000, v150
	s_nop 1
	v_addc_co_u32_e32 v165, vcc, 0, v151, vcc
	global_load_dwordx4 v[234:237], v[164:165], off offset:16 nt
	global_load_dwordx4 v[238:241], v[164:165], off nt
	global_load_dwordx4 v[242:245], v[164:165], off offset:528 nt
	global_load_dwordx4 v[154:157], v[164:165], off offset:512 nt
	s_waitcnt vmcnt(15)
	v_pk_fma_f32 v[108:109], v[108:109], v[140:141], v[180:181]
	v_pk_fma_f32 v[106:107], v[106:107], v[138:139], v[178:179]
	v_add_co_u32_e32 v164, vcc, 0x100000, v150
	s_nop 1
	v_addc_co_u32_e32 v165, vcc, 0, v151, vcc
	global_load_dwordx4 v[178:181], v[164:165], off nt
	s_waitcnt vmcnt(15)
	v_pk_fma_f32 v[112:113], v[112:113], v[144:145], v[184:185]
	v_pk_fma_f32 v[110:111], v[110:111], v[142:143], v[182:183]
	global_load_dwordx4 v[182:185], v[164:165], off offset:16 nt
	s_waitcnt vmcnt(15)
	v_pk_fma_f32 v[0:1], v[0:1], v[130:131], v[186:187]
	v_pk_fma_f32 v[2:3], v[2:3], v[132:133], v[188:189]
	global_load_dwordx4 v[186:189], v[164:165], off offset:528 nt
	s_waitcnt vmcnt(15)
	v_pk_fma_f32 v[6:7], v[6:7], v[136:137], v[192:193]
	v_pk_fma_f32 v[4:5], v[4:5], v[134:135], v[190:191]
	global_load_dwordx4 v[190:193], v[164:165], off offset:512 nt
	s_waitcnt vmcnt(15)
	v_pk_fma_f32 v[116:117], v[116:117], v[140:141], v[200:201]
	v_pk_fma_f32 v[114:115], v[114:115], v[138:139], v[198:199]
	v_add_co_u32_e32 v164, vcc, 0x120000, v150
	s_nop 1
	v_addc_co_u32_e32 v165, vcc, 0, v151, vcc
	global_load_dwordx4 v[198:201], v[164:165], off nt
	s_waitcnt vmcnt(15)
	v_pk_fma_f32 v[120:121], v[120:121], v[144:145], v[204:205]
	v_pk_fma_f32 v[118:119], v[118:119], v[142:143], v[202:203]
	global_load_dwordx4 v[202:205], v[164:165], off offset:16 nt
	s_waitcnt vmcnt(15)
	v_pk_fma_f32 v[8:9], v[8:9], v[130:131], v[206:207]
	v_pk_fma_f32 v[10:11], v[10:11], v[132:133], v[208:209]
	global_load_dwordx4 v[206:209], v[164:165], off offset:528 nt
	s_waitcnt vmcnt(15)
	v_pk_fma_f32 v[14:15], v[14:15], v[136:137], v[216:217]
	v_pk_fma_f32 v[12:13], v[12:13], v[134:135], v[214:215]
	global_load_dwordx4 v[214:217], v[164:165], off offset:512 nt
	s_waitcnt vmcnt(15)
	v_pk_fma_f32 v[124:125], v[124:125], v[140:141], v[220:221]
	v_pk_fma_f32 v[122:123], v[122:123], v[138:139], v[218:219]
	v_add_co_u32_e32 v164, vcc, 0x140000, v150
	s_nop 1
	v_addc_co_u32_e32 v165, vcc, 0, v151, vcc
	global_load_dwordx4 v[218:221], v[164:165], off nt
	s_waitcnt vmcnt(15)
	v_pk_fma_f32 v[128:129], v[128:129], v[144:145], v[224:225]
	v_pk_fma_f32 v[126:127], v[126:127], v[142:143], v[222:223]
	global_load_dwordx4 v[222:225], v[164:165], off offset:16 nt
	s_waitcnt vmcnt(15)
	v_pk_fma_f32 v[20:21], v[20:21], v[130:131], v[226:227]
	v_pk_fma_f32 v[22:23], v[22:23], v[132:133], v[228:229]
	global_load_dwordx4 v[226:229], v[164:165], off offset:528 nt
	s_waitcnt vmcnt(15)
	v_pk_fma_f32 v[26:27], v[26:27], v[136:137], v[232:233]
	v_pk_fma_f32 v[24:25], v[24:25], v[134:135], v[230:231]
	global_load_dwordx4 v[230:233], v[164:165], off offset:512 nt
	s_waitcnt vmcnt(15)
	v_pk_fma_f32 v[90:91], v[90:91], v[140:141], v[236:237]
	v_pk_fma_f32 v[88:89], v[88:89], v[138:139], v[234:235]
	v_add_co_u32_e32 v164, vcc, 0x160000, v150
	s_nop 1
	v_addc_co_u32_e32 v165, vcc, 0, v151, vcc
	global_load_dwordx4 v[234:237], v[164:165], off nt
	s_waitcnt vmcnt(15)
	v_pk_fma_f32 v[94:95], v[94:95], v[144:145], v[240:241]
	v_pk_fma_f32 v[92:93], v[92:93], v[142:143], v[238:239]
	global_load_dwordx4 v[238:241], v[164:165], off offset:16 nt
	s_waitcnt vmcnt(15)
	v_pk_fma_f32 v[38:39], v[38:39], v[132:133], v[244:245]
	v_pk_fma_f32 v[36:37], v[36:37], v[130:131], v[242:243]
	global_load_dwordx4 v[242:245], v[164:165], off offset:528 nt
	s_waitcnt vmcnt(15)
	v_pk_fma_f32 v[42:43], v[42:43], v[136:137], v[156:157]
	v_pk_fma_f32 v[40:41], v[40:41], v[134:135], v[154:155]
	global_load_dwordx4 v[154:157], v[164:165], off offset:512 nt
	s_waitcnt vmcnt(15)
	v_pk_fma_f32 v[104:105], v[104:105], v[144:145], v[180:181]
	v_pk_fma_f32 v[102:103], v[102:103], v[142:143], v[178:179]
	s_waitcnt vmcnt(14)
	v_pk_fma_f32 v[100:101], v[100:101], v[140:141], v[184:185]
	v_pk_fma_f32 v[98:99], v[98:99], v[138:139], v[182:183]
	s_waitcnt vmcnt(13)
	v_pk_fma_f32 v[56:57], v[56:57], v[130:131], v[186:187]
	v_pk_fma_f32 v[58:59], v[58:59], v[132:133], v[188:189]
	s_waitcnt vmcnt(12)
	v_pk_fma_f32 v[62:63], v[62:63], v[136:137], v[192:193]
	v_pk_fma_f32 v[60:61], v[60:61], v[134:135], v[190:191]
	s_waitcnt vmcnt(11)
	v_pk_fma_f32 v[86:87], v[86:87], v[144:145], v[200:201]
	v_pk_fma_f32 v[84:85], v[84:85], v[142:143], v[198:199]
	s_waitcnt vmcnt(10)
	v_pk_fma_f32 v[82:83], v[82:83], v[140:141], v[204:205]
	v_pk_fma_f32 v[80:81], v[80:81], v[138:139], v[202:203]
	s_waitcnt vmcnt(9)
	v_pk_fma_f32 v[72:73], v[72:73], v[130:131], v[206:207]
	v_pk_fma_f32 v[74:75], v[74:75], v[132:133], v[208:209]
	s_waitcnt vmcnt(8)
	v_pk_fma_f32 v[78:79], v[78:79], v[136:137], v[216:217]
	v_pk_fma_f32 v[76:77], v[76:77], v[134:135], v[214:215]
	s_waitcnt vmcnt(7)
	v_pk_fma_f32 v[70:71], v[70:71], v[144:145], v[220:221]
	v_pk_fma_f32 v[68:69], v[68:69], v[142:143], v[218:219]
	s_waitcnt vmcnt(6)
	v_pk_fma_f32 v[66:67], v[66:67], v[140:141], v[224:225]
	v_pk_fma_f32 v[64:65], v[64:65], v[138:139], v[222:223]
	s_waitcnt vmcnt(5)
	v_pk_fma_f32 v[50:51], v[50:51], v[132:133], v[228:229]
	v_pk_fma_f32 v[48:49], v[48:49], v[130:131], v[226:227]
	s_waitcnt vmcnt(4)
	v_pk_fma_f32 v[54:55], v[54:55], v[136:137], v[232:233]
	v_pk_fma_f32 v[52:53], v[52:53], v[134:135], v[230:231]
	s_waitcnt vmcnt(3)
	v_pk_fma_f32 v[46:47], v[46:47], v[144:145], v[236:237]
	v_pk_fma_f32 v[44:45], v[44:45], v[142:143], v[234:235]
	s_waitcnt vmcnt(2)
	v_pk_fma_f32 v[34:35], v[34:35], v[140:141], v[240:241]
	v_pk_fma_f32 v[32:33], v[32:33], v[138:139], v[238:239]
	s_waitcnt vmcnt(1)
	v_pk_fma_f32 v[18:19], v[18:19], v[132:133], v[244:245]
	v_pk_fma_f32 v[16:17], v[16:17], v[130:131], v[242:243]
	s_waitcnt vmcnt(0)
	v_pk_fma_f32 v[28:29], v[28:29], v[134:135], v[154:155]
	v_pk_fma_f32 v[30:31], v[30:31], v[136:137], v[156:157]
	s_mov_b64 s[0:1], 0x160000
	s_branch .Lmy_pad_0
	s_nop 0
	s_nop 0
	s_nop 0
	s_nop 0
	s_nop 0
	s_nop 0
	s_nop 0
	s_nop 0
	s_nop 0
	s_nop 0
	s_nop 0
	s_nop 0
	s_nop 0
	s_nop 0
	s_nop 0
	s_nop 0
	s_nop 0
	s_nop 0
	s_nop 0
	s_nop 0
	s_nop 0
	s_nop 0
	s_nop 0
	s_nop 0
	s_nop 0
	s_nop 0
	s_nop 0
	s_nop 0
	s_nop 0
	s_nop 0
	s_nop 0
	s_nop 0
	s_nop 0
	s_nop 0
	s_nop 0
	s_nop 0
	s_nop 0
	s_nop 0
	s_nop 0
	s_nop 0
	s_nop 0
	s_nop 0
	s_nop 0
	s_nop 0
	s_nop 0
	s_nop 0
	s_nop 0
	s_nop 0

.LBB0_1385:
	s_or_b64 exec, exec, s[8:9]
	s_mov_b64 s[2:3], 0x20000
	v_ashrrev_i32_e32 v149, 31, v148
	v_lshlrev_b64 v[134:135], 13, v[148:149]
	v_lshl_add_u64 v[134:135], s[96:97], 0, v[134:135]
	v_lshl_add_u64 v[134:135], v[162:163], 2, v[134:135]
	v_mov_b64_e32 v[136:137], v[134:135]
	flat_store_dwordx4 v[136:137], v[110:113] nt
	flat_store_dwordx4 v[136:137], v[106:109] offset:16 nt
	flat_store_dwordx4 v[136:137], v[4:7] offset:512 nt
	flat_store_dwordx4 v[136:137], v[0:3] offset:528 nt
	v_lshl_add_u64 v[136:137], v[134:135], 0, s[2:3]
	s_mov_b64 s[2:3], 0x40000
	flat_store_dwordx4 v[136:137], v[118:121] nt
	flat_store_dwordx4 v[136:137], v[114:117] offset:16 nt
	flat_store_dwordx4 v[136:137], v[12:15] offset:512 nt
	flat_store_dwordx4 v[136:137], v[8:11] offset:528 nt
	v_lshl_add_u64 v[136:137], v[134:135], 0, s[2:3]
	s_mov_b64 s[2:3], 0x60000
	flat_store_dwordx4 v[136:137], v[126:129] nt
	flat_store_dwordx4 v[136:137], v[122:125] offset:16 nt
	flat_store_dwordx4 v[136:137], v[24:27] offset:512 nt
	flat_store_dwordx4 v[136:137], v[20:23] offset:528 nt
	v_lshl_add_u64 v[136:137], v[134:135], 0, s[2:3]
	s_mov_b64 s[2:3], 0x100000
	flat_store_dwordx4 v[136:137], v[92:95] nt
	flat_store_dwordx4 v[136:137], v[88:91] offset:16 nt
	flat_store_dwordx4 v[136:137], v[40:43] offset:512 nt
	flat_store_dwordx4 v[136:137], v[36:39] offset:528 nt
	v_lshl_add_u64 v[136:137], v[134:135], 0, s[2:3]
	s_mov_b64 s[2:3], 0x120000
	flat_store_dwordx4 v[136:137], v[102:105] nt
	flat_store_dwordx4 v[136:137], v[98:101] offset:16 nt
	flat_store_dwordx4 v[136:137], v[60:63] offset:512 nt
	flat_store_dwordx4 v[136:137], v[56:59] offset:528 nt
	v_lshl_add_u64 v[136:137], v[134:135], 0, s[2:3]
	s_mov_b64 s[2:3], 0x140000
	flat_store_dwordx4 v[136:137], v[84:87] nt
	flat_store_dwordx4 v[136:137], v[80:83] offset:16 nt
	flat_store_dwordx4 v[136:137], v[76:79] offset:512 nt
	flat_store_dwordx4 v[136:137], v[72:75] offset:528 nt
	v_lshl_add_u64 v[136:137], v[134:135], 0, s[2:3]
	s_mov_b64 s[2:3], 0x160000
	v_lshl_add_u64 v[134:135], v[134:135], 0, s[2:3]
	flat_store_dwordx4 v[136:137], v[68:71] nt
	flat_store_dwordx4 v[136:137], v[64:67] offset:16 nt
	flat_store_dwordx4 v[136:137], v[52:55] offset:512 nt
	flat_store_dwordx4 v[136:137], v[48:51] offset:528 nt
	s_cmp_gt_u32 s40, 63
	flat_store_dwordx4 v[134:135], v[44:47] nt
	flat_store_dwordx4 v[134:135], v[32:35] offset:16 nt
	flat_store_dwordx4 v[134:135], v[28:31] offset:512 nt
	flat_store_dwordx4 v[134:135], v[16:19] offset:528 nt
	s_cbranch_scc1 .LBB0_1391
	s_lshl_b32 s8, s51, 4
	s_lshl_b32 s2, s60, 7
	s_ashr_i32 s9, s8, 31
	s_addk_i32 s2, 0x80
	s_lshl_b64 s[8:9], s[8:9], 2
	v_readlane_b32 s3, v252, 39
	s_add_u32 s8, s3, s8
	v_readlane_b32 s3, v252, 40
	s_addc_u32 s9, s3, s9
	s_mov_b32 s3, 0x100001
	s_branch .LBB0_1388

.LBB0_1416:
	s_cmp_lt_i32 s43, 32
	v_lshl_add_u32 v164, s43, 8, v154
	v_lshl_or_b32 v162, s44, 8, v156
	s_cselect_b32 s2, s87, 0x6000
	s_cselect_b32 s22, s68, s96
	s_cselect_b32 s23, s69, s97
	s_cmp_gt_i32 s43, 15
	v_ashrrev_i32_e32 v165, 31, v164
	s_cselect_b32 s2, s2, 0
	v_ashrrev_i32_e32 v163, 31, v162
	v_lshlrev_b64 v[132:133], 11, v[164:165]
	s_lshl_b32 s2, s2, 2
	v_lshl_add_u64 v[132:133], v[132:133], 0, v[162:163]
	s_add_u32 s2, s49, s2
	v_lshlrev_b64 v[152:153], 2, v[132:133]
	s_addc_u32 s3, s50, 0
	v_lshl_add_u64 v[166:167], s[96:97], 0, v[152:153]
	v_lshl_add_u64 v[130:131], v[162:163], 2, s[2:3]
	global_load_dwordx4 v[142:145], v[130:131], off
	global_load_dwordx4 v[138:141], v[130:131], off offset:64
	global_load_dwordx4 v[134:137], v[130:131], off offset:512
	global_load_dwordx4 v[130:133], v[130:131], off offset:576
	v_lshl_add_u64 v[168:169], s[22:23], 0, v[152:153]
	s_and_b64 vcc, exec, s[0:1]
	s_mov_b64 s[0:1], -1
	v_mov_b64_e32 v[240:241], v[166:167]
	global_load_dwordx4 v[220:223], v[240:241], off nt
	global_load_dwordx4 v[224:227], v[240:241], off offset:64 nt
	global_load_dwordx4 v[228:231], v[240:241], off offset:512 nt
	global_load_dwordx4 v[232:235], v[240:241], off offset:576 nt
	s_mov_b64 s[2:3], 0x20000
	v_lshl_add_u64 v[240:241], v[166:167], 0, s[2:3]
	global_load_dwordx4 v[236:239], v[240:241], off nt
	global_load_dwordx4 v[170:173], v[240:241], off offset:64 nt
	global_load_dwordx4 v[174:177], v[240:241], off offset:512 nt
	global_load_dwordx4 v[178:181], v[240:241], off offset:576 nt
	s_mov_b64 s[2:3], 0x40000
	v_lshl_add_u64 v[240:241], v[166:167], 0, s[2:3]
	global_load_dwordx4 v[182:185], v[240:241], off nt
	global_load_dwordx4 v[186:189], v[240:241], off offset:64 nt
	global_load_dwordx4 v[190:193], v[240:241], off offset:512 nt
	global_load_dwordx4 v[202:205], v[240:241], off offset:576 nt
	s_mov_b64 s[2:3], 0x60000
	v_lshl_add_u64 v[240:241], v[166:167], 0, s[2:3]
	global_load_dwordx4 v[206:209], v[240:241], off nt
	global_load_dwordx4 v[214:217], v[240:241], off offset:64 nt
	global_load_dwordx4 v[158:161], v[240:241], off offset:512 nt
	s_waitcnt vmcnt(14)
	v_pk_fma_f32 v[222:223], v[128:129], v[144:145], v[222:223]
	v_pk_fma_f32 v[220:221], v[126:127], v[142:143], v[220:221]
	v_mov_b64_e32 v[242:243], v[168:169]
	global_store_dwordx4 v[242:243], v[220:223], off nt
	s_nop 1
	global_load_dwordx4 v[220:223], v[240:241], off offset:576 nt
	s_waitcnt vmcnt(15)
	v_pk_fma_f32 v[226:227], v[124:125], v[140:141], v[226:227]
	v_pk_fma_f32 v[224:225], v[122:123], v[138:139], v[224:225]
	global_store_dwordx4 v[242:243], v[224:227], off offset:64 nt
	s_mov_b64 s[2:3], 0x100000
	v_lshl_add_u64 v[240:241], v[166:167], 0, s[2:3]
	global_load_dwordx4 v[224:227], v[240:241], off nt
	s_waitcnt vmcnt(16)
	v_pk_fma_f32 v[230:231], v[120:121], v[136:137], v[230:231]
	v_pk_fma_f32 v[228:229], v[118:119], v[134:135], v[228:229]
	global_store_dwordx4 v[242:243], v[228:231], off offset:512 nt
	s_nop 1
	global_load_dwordx4 v[228:231], v[240:241], off offset:64 nt
	s_waitcnt vmcnt(17)
	v_pk_fma_f32 v[234:235], v[108:109], v[132:133], v[234:235]
	v_pk_fma_f32 v[232:233], v[106:107], v[130:131], v[232:233]
	global_store_dwordx4 v[242:243], v[232:235], off offset:576 nt
	s_nop 1
	global_load_dwordx4 v[232:235], v[240:241], off offset:512 nt
	s_waitcnt vmcnt(18)
	v_pk_fma_f32 v[238:239], v[116:117], v[144:145], v[238:239]
	v_pk_fma_f32 v[236:237], v[114:115], v[142:143], v[236:237]
	s_mov_b64 s[2:3], 0x20000
	v_lshl_add_u64 v[242:243], v[168:169], 0, s[2:3]
	global_store_dwordx4 v[242:243], v[236:239], off nt
	s_nop 1
	global_load_dwordx4 v[236:239], v[240:241], off offset:576 nt
	s_waitcnt vmcnt(19)
	v_pk_fma_f32 v[172:173], v[112:113], v[140:141], v[172:173]
	v_pk_fma_f32 v[170:171], v[110:111], v[138:139], v[170:171]
	global_store_dwordx4 v[242:243], v[170:173], off offset:64 nt
	s_mov_b64 s[2:3], 0x120000
	v_lshl_add_u64 v[240:241], v[166:167], 0, s[2:3]
	global_load_dwordx4 v[170:173], v[240:241], off nt
	s_waitcnt vmcnt(20)
	v_pk_fma_f32 v[176:177], v[104:105], v[136:137], v[176:177]
	v_pk_fma_f32 v[174:175], v[102:103], v[134:135], v[174:175]
	global_store_dwordx4 v[242:243], v[174:177], off offset:512 nt
	s_nop 1
	global_load_dwordx4 v[174:177], v[240:241], off offset:64 nt
	s_waitcnt vmcnt(21)
	v_pk_fma_f32 v[180:181], v[90:91], v[132:133], v[180:181]
	v_pk_fma_f32 v[178:179], v[88:89], v[130:131], v[178:179]
	global_store_dwordx4 v[242:243], v[178:181], off offset:576 nt
	s_nop 1
	global_load_dwordx4 v[178:181], v[240:241], off offset:512 nt
	s_waitcnt vmcnt(22)
	v_pk_fma_f32 v[184:185], v[100:101], v[144:145], v[184:185]
	v_pk_fma_f32 v[182:183], v[98:99], v[142:143], v[182:183]
	s_mov_b64 s[2:3], 0x40000
	v_lshl_add_u64 v[242:243], v[168:169], 0, s[2:3]
	global_store_dwordx4 v[242:243], v[182:185], off nt
	s_nop 1
	global_load_dwordx4 v[182:185], v[240:241], off offset:576 nt
	s_waitcnt vmcnt(23)
	v_pk_fma_f32 v[188:189], v[94:95], v[140:141], v[188:189]
	v_pk_fma_f32 v[186:187], v[92:93], v[138:139], v[186:187]
	global_store_dwordx4 v[242:243], v[186:189], off offset:64 nt
	s_mov_b64 s[2:3], 0x140000
	v_lshl_add_u64 v[240:241], v[166:167], 0, s[2:3]
	global_load_dwordx4 v[186:189], v[240:241], off nt
	s_waitcnt vmcnt(24)
	v_pk_fma_f32 v[192:193], v[86:87], v[136:137], v[192:193]
	v_pk_fma_f32 v[190:191], v[84:85], v[134:135], v[190:191]
	global_store_dwordx4 v[242:243], v[190:193], off offset:512 nt
	s_nop 1
	global_load_dwordx4 v[190:193], v[240:241], off offset:64 nt
	s_waitcnt vmcnt(25)
	v_pk_fma_f32 v[204:205], v[74:75], v[132:133], v[204:205]
	v_pk_fma_f32 v[202:203], v[72:73], v[130:131], v[202:203]
	global_store_dwordx4 v[242:243], v[202:205], off offset:576 nt
	s_nop 1
	global_load_dwordx4 v[202:205], v[240:241], off offset:512 nt
	s_waitcnt vmcnt(26)
	v_pk_fma_f32 v[208:209], v[82:83], v[144:145], v[208:209]
	v_pk_fma_f32 v[206:207], v[80:81], v[142:143], v[206:207]
	s_mov_b64 s[2:3], 0x60000
	v_lshl_add_u64 v[242:243], v[168:169], 0, s[2:3]
	global_store_dwordx4 v[242:243], v[206:209], off nt
	s_nop 1
	global_load_dwordx4 v[206:209], v[240:241], off offset:576 nt
	s_waitcnt vmcnt(27)
	v_pk_fma_f32 v[216:217], v[78:79], v[140:141], v[216:217]
	v_pk_fma_f32 v[214:215], v[76:77], v[138:139], v[214:215]
	global_store_dwordx4 v[242:243], v[214:217], off offset:64 nt
	s_mov_b64 s[2:3], 0x160000
	v_lshl_add_u64 v[240:241], v[166:167], 0, s[2:3]
	global_load_dwordx4 v[214:217], v[240:241], off nt
	s_waitcnt vmcnt(28)
	v_pk_fma_f32 v[160:161], v[70:71], v[136:137], v[160:161]
	v_pk_fma_f32 v[158:159], v[68:69], v[134:135], v[158:159]
	global_store_dwordx4 v[242:243], v[158:161], off offset:512 nt
	s_nop 1
	global_load_dwordx4 v[158:161], v[240:241], off offset:64 nt
	s_waitcnt vmcnt(28)
	v_pk_fma_f32 v[222:223], v[66:67], v[132:133], v[222:223]
	v_pk_fma_f32 v[220:221], v[64:65], v[130:131], v[220:221]
	global_store_dwordx4 v[242:243], v[220:223], off offset:576 nt
	s_nop 1
	global_load_dwordx4 v[220:223], v[240:241], off offset:512 nt
	s_waitcnt vmcnt(28)
	v_pk_fma_f32 v[226:227], v[62:63], v[144:145], v[226:227]
	v_pk_fma_f32 v[224:225], v[60:61], v[142:143], v[224:225]
	s_mov_b64 s[2:3], 0x100000
	v_lshl_add_u64 v[242:243], v[168:169], 0, s[2:3]
	global_store_dwordx4 v[242:243], v[224:227], off nt
	s_nop 1
	global_load_dwordx4 v[224:227], v[240:241], off offset:576 nt
	s_waitcnt vmcnt(28)
	v_pk_fma_f32 v[230:231], v[58:59], v[140:141], v[230:231]
	v_pk_fma_f32 v[228:229], v[56:57], v[138:139], v[228:229]
	global_store_dwordx4 v[242:243], v[228:231], off offset:64 nt
	s_waitcnt vmcnt(27)
	v_pk_fma_f32 v[234:235], v[54:55], v[136:137], v[234:235]
	v_pk_fma_f32 v[232:233], v[52:53], v[134:135], v[232:233]
	global_store_dwordx4 v[242:243], v[232:235], off offset:512 nt
	s_waitcnt vmcnt(26)
	v_pk_fma_f32 v[238:239], v[42:43], v[132:133], v[238:239]
	v_pk_fma_f32 v[236:237], v[40:41], v[130:131], v[236:237]
	global_store_dwordx4 v[242:243], v[236:239], off offset:576 nt
	s_waitcnt vmcnt(25)
	v_pk_fma_f32 v[172:173], v[50:51], v[144:145], v[172:173]
	v_pk_fma_f32 v[170:171], v[48:49], v[142:143], v[170:171]
	s_mov_b64 s[2:3], 0x120000
	v_lshl_add_u64 v[242:243], v[168:169], 0, s[2:3]
	global_store_dwordx4 v[242:243], v[170:173], off nt
	s_waitcnt vmcnt(24)
	v_pk_fma_f32 v[176:177], v[46:47], v[140:141], v[176:177]
	v_pk_fma_f32 v[174:175], v[44:45], v[138:139], v[174:175]
	global_store_dwordx4 v[242:243], v[174:177], off offset:64 nt
	s_waitcnt vmcnt(23)
	v_pk_fma_f32 v[180:181], v[38:39], v[136:137], v[180:181]
	v_pk_fma_f32 v[178:179], v[36:37], v[134:135], v[178:179]
	global_store_dwordx4 v[242:243], v[178:181], off offset:512 nt
	s_waitcnt vmcnt(22)
	v_pk_fma_f32 v[184:185], v[26:27], v[132:133], v[184:185]
	v_pk_fma_f32 v[182:183], v[24:25], v[130:131], v[182:183]
	global_store_dwordx4 v[242:243], v[182:185], off offset:576 nt
	s_waitcnt vmcnt(21)
	v_pk_fma_f32 v[188:189], v[34:35], v[144:145], v[188:189]
	v_pk_fma_f32 v[186:187], v[32:33], v[142:143], v[186:187]
	s_mov_b64 s[2:3], 0x140000
	v_lshl_add_u64 v[242:243], v[168:169], 0, s[2:3]
	global_store_dwordx4 v[242:243], v[186:189], off nt
	s_waitcnt vmcnt(20)
	v_pk_fma_f32 v[192:193], v[30:31], v[140:141], v[192:193]
	v_pk_fma_f32 v[190:191], v[28:29], v[138:139], v[190:191]
	global_store_dwordx4 v[242:243], v[190:193], off offset:64 nt
	s_waitcnt vmcnt(19)
	v_pk_fma_f32 v[204:205], v[22:23], v[136:137], v[204:205]
	v_pk_fma_f32 v[202:203], v[20:21], v[134:135], v[202:203]
	global_store_dwordx4 v[242:243], v[202:205], off offset:512 nt
	s_waitcnt vmcnt(18)
	v_pk_fma_f32 v[208:209], v[10:11], v[132:133], v[208:209]
	v_pk_fma_f32 v[206:207], v[8:9], v[130:131], v[206:207]
	global_store_dwordx4 v[242:243], v[206:209], off offset:576 nt
	s_waitcnt vmcnt(17)
	v_pk_fma_f32 v[216:217], v[18:19], v[144:145], v[216:217]
	v_pk_fma_f32 v[214:215], v[16:17], v[142:143], v[214:215]
	s_mov_b64 s[2:3], 0x160000
	v_lshl_add_u64 v[242:243], v[168:169], 0, s[2:3]
	global_store_dwordx4 v[242:243], v[214:217], off nt
	s_waitcnt vmcnt(16)
	v_pk_fma_f32 v[160:161], v[14:15], v[140:141], v[160:161]
	v_pk_fma_f32 v[158:159], v[12:13], v[138:139], v[158:159]
	global_store_dwordx4 v[242:243], v[158:161], off offset:64 nt
	s_waitcnt vmcnt(15)
	v_pk_fma_f32 v[222:223], v[6:7], v[136:137], v[222:223]
	v_pk_fma_f32 v[220:221], v[4:5], v[134:135], v[220:221]
	global_store_dwordx4 v[242:243], v[220:223], off offset:512 nt
	s_waitcnt vmcnt(14)
	v_pk_fma_f32 v[226:227], v[2:3], v[132:133], v[226:227]
	v_pk_fma_f32 v[224:225], v[0:1], v[130:131], v[224:225]
	global_store_dwordx4 v[242:243], v[224:227], off offset:576 nt
	s_mov_b64 s[2:3], 0x160000
	s_cbranch_vccnz .LBB0_1401
	s_andn2_b64 vcc, exec, s[8:9]
	s_cbranch_vccnz .LBB0_1400
	s_barrier
	s_branch .LBB0_1400
